# in-proj epilogue batching plus one s_nop so the later K-loops keep their earlier code placement
# baseline (speedup 1.0000x reference)
.LBB0_120:
	s_lshl_b32 s8, s8, 8
	v_mov_b32_e32 v172, v157
	v_mov_b32_e32 v130, v1
	s_add_i32 s8, s8, s62
	v_and_b32_e32 v134, 64, v169
	v_add_u32_e32 v154, s8, v130
	v_mov_b32_e32 v131, v172
	v_mov_b32_e32 v130, v154
	v_add_u32_e32 v134, 64, v134
	v_lshlrev_b32_e32 v132, 3, v131
	v_xor_b32_e32 v131, 16, v169
	v_cmp_lt_i32_e32 vcc, v131, v134
	v_ashrrev_i32_e32 v133, 31, v132
	v_lshl_add_u64 v[132:133], v[132:133], 2, s[10:11]
	v_cndmask_b32_e32 v131, v169, v131, vcc
	v_lshlrev_b32_e32 v173, 2, v131
	v_xor_b32_e32 v131, 32, v169
	v_cmp_lt_i32_e32 vcc, v131, v134
	v_cndmask_b32_e32 v131, v169, v131, vcc
	v_lshlrev_b32_e32 v155, 2, v131
	v_ashrrev_i32_e32 v131, 31, v130
	v_lshlrev_b64 v[130:131], 7, v[130:131]
	v_lshl_add_u64 v[130:131], v[132:133], 0, v[130:131]
	s_mov_b64 s[8:9], 0x1000
	v_lshl_add_u64 v[132:133], v[130:131], 0, s[8:9]
	global_load_dwordx4 v[174:177], v[130:131], off
	global_load_dwordx4 v[178:181], v[130:131], off offset:16
	global_load_dwordx4 v[182:185], v[130:131], off offset:2048
	global_load_dwordx4 v[186:189], v[130:131], off offset:2064
	s_mov_b64 s[8:9], 0x4000
	v_lshl_add_u64 v[134:135], v[130:131], 0, s[8:9]
	global_load_dwordx4 v[190:193], v[132:133], off
	global_load_dwordx4 v[194:197], v[132:133], off offset:16
	global_load_dwordx4 v[198:201], v[132:133], off offset:2048
	global_load_dwordx4 v[202:205], v[132:133], off offset:2064
	s_mov_b64 s[8:9], 0x5000
	v_lshl_add_u64 v[136:137], v[130:131], 0, s[8:9]
	global_load_dwordx4 v[206:209], v[134:135], off
	global_load_dwordx4 v[210:213], v[134:135], off offset:16
	global_load_dwordx4 v[214:217], v[134:135], off offset:2048
	global_load_dwordx4 v[218:221], v[134:135], off offset:2064
	global_load_dwordx4 v[222:225], v[136:137], off
	global_load_dwordx4 v[226:229], v[136:137], off offset:16
	global_load_dwordx4 v[230:233], v[136:137], off offset:2048
	global_load_dwordx4 v[234:237], v[136:137], off offset:2064
	v_mov_b32_e32 v166, 0x358637bd
	s_waitcnt vmcnt(0)
	v_add_f32_e32 v174, v174, v175
	v_add_f32_e32 v178, v178, v179
	v_add_f32_e32 v182, v182, v183
	v_add_f32_e32 v186, v186, v187
	v_add_f32_e32 v176, v176, v177
	v_add_f32_e32 v180, v180, v181
	v_add_f32_e32 v184, v184, v185
	v_add_f32_e32 v188, v188, v189
	v_add_f32_e32 v174, v174, v176
	v_add_f32_e32 v178, v178, v180
	v_add_f32_e32 v182, v182, v184
	v_add_f32_e32 v186, v186, v188
	v_add_f32_e32 v175, v174, v178
	v_add_f32_e32 v174, v182, v186
	v_add_f32_e32 v190, v190, v191
	v_add_f32_e32 v194, v194, v195
	v_add_f32_e32 v198, v198, v199
	v_add_f32_e32 v202, v202, v203
	v_add_f32_e32 v192, v192, v193
	v_add_f32_e32 v196, v196, v197
	v_add_f32_e32 v200, v200, v201
	v_add_f32_e32 v204, v204, v205
	v_add_f32_e32 v190, v190, v192
	v_add_f32_e32 v194, v194, v196
	v_add_f32_e32 v198, v198, v200
	v_add_f32_e32 v202, v202, v204
	v_add_f32_e32 v191, v190, v194
	v_add_f32_e32 v190, v198, v202
	v_add_f32_e32 v206, v206, v207
	v_add_f32_e32 v210, v210, v211
	v_add_f32_e32 v214, v214, v215
	v_add_f32_e32 v218, v218, v219
	v_add_f32_e32 v208, v208, v209
	v_add_f32_e32 v212, v212, v213
	v_add_f32_e32 v216, v216, v217
	v_add_f32_e32 v220, v220, v221
	v_add_f32_e32 v206, v206, v208
	v_add_f32_e32 v210, v210, v212
	v_add_f32_e32 v214, v214, v216
	v_add_f32_e32 v218, v218, v220
	v_add_f32_e32 v207, v206, v210
	v_add_f32_e32 v206, v214, v218
	v_add_f32_e32 v222, v222, v223
	v_add_f32_e32 v226, v226, v227
	v_add_f32_e32 v230, v230, v231
	v_add_f32_e32 v234, v234, v235
	v_add_f32_e32 v224, v224, v225
	v_add_f32_e32 v228, v228, v229
	v_add_f32_e32 v232, v232, v233
	v_add_f32_e32 v236, v236, v237
	v_add_f32_e32 v222, v222, v224
	v_add_f32_e32 v226, v226, v228
	v_add_f32_e32 v230, v230, v232
	v_add_f32_e32 v234, v234, v236
	v_add_f32_e32 v223, v222, v226
	v_add_f32_e32 v222, v230, v234
	ds_bpermute_b32 v179, v173, v175
	ds_bpermute_b32 v178, v173, v174
	ds_bpermute_b32 v195, v173, v191
	ds_bpermute_b32 v194, v173, v190
	ds_bpermute_b32 v211, v173, v207
	ds_bpermute_b32 v210, v173, v206
	ds_bpermute_b32 v227, v173, v223
	ds_bpermute_b32 v226, v173, v222
	s_waitcnt lgkmcnt(0)
	v_pk_add_f32 v[174:175], v[174:175], v[178:179]
	v_pk_add_f32 v[190:191], v[190:191], v[194:195]
	v_pk_add_f32 v[206:207], v[206:207], v[210:211]
	v_pk_add_f32 v[222:223], v[222:223], v[226:227]
	ds_bpermute_b32 v179, v155, v175
	ds_bpermute_b32 v178, v155, v174
	ds_bpermute_b32 v195, v155, v191
	ds_bpermute_b32 v194, v155, v190
	ds_bpermute_b32 v211, v155, v207
	ds_bpermute_b32 v210, v155, v206
	ds_bpermute_b32 v227, v155, v223
	ds_bpermute_b32 v226, v155, v222
	s_waitcnt lgkmcnt(0)
	v_pk_add_f32 v[174:175], v[174:175], v[178:179]
	v_pk_add_f32 v[190:191], v[190:191], v[194:195]
	v_pk_add_f32 v[206:207], v[206:207], v[210:211]
	v_pk_add_f32 v[222:223], v[222:223], v[226:227]
	v_pk_fma_f32 v[174:175], v[174:175], s[36:37], v[166:167] op_sel_hi:[1,0,0]
	v_pk_fma_f32 v[190:191], v[190:191], s[36:37], v[166:167] op_sel_hi:[1,0,0]
	v_pk_fma_f32 v[206:207], v[206:207], s[36:37], v[166:167] op_sel_hi:[1,0,0]
	v_pk_fma_f32 v[222:223], v[222:223], s[36:37], v[166:167] op_sel_hi:[1,0,0]
	v_mul_f32_e32 v178, 0x4b800000, v175
	v_cmp_gt_f32_e64 s[8:9], s69, v175
	v_cmp_gt_f32_e32 vcc, s69, v174
	s_nop 0
	v_cndmask_b32_e64 v175, v175, v178, s[8:9]
	v_rsq_f32_e32 v175, v175
	s_nop 0
	v_mul_f32_e32 v178, 0x45800000, v175
	v_cndmask_b32_e64 v158, v175, v178, s[8:9]
	v_mul_f32_e32 v175, 0x4b800000, v174
	v_cndmask_b32_e32 v174, v174, v175, vcc
	v_rsq_f32_e32 v174, v174
	s_nop 0
	v_mul_f32_e32 v175, 0x45800000, v174
	v_cndmask_b32_e32 v156, v174, v175, vcc
	v_mul_f32_e32 v194, 0x4b800000, v191
	v_cmp_gt_f32_e64 s[8:9], s69, v191
	v_cmp_gt_f32_e32 vcc, s69, v190
	s_nop 0
	v_cndmask_b32_e64 v191, v191, v194, s[8:9]
	v_rsq_f32_e32 v191, v191
	s_nop 0
	v_mul_f32_e32 v194, 0x45800000, v191
	v_cndmask_b32_e64 v162, v191, v194, s[8:9]
	v_mul_f32_e32 v191, 0x4b800000, v190
	v_cndmask_b32_e32 v190, v190, v191, vcc
	v_rsq_f32_e32 v190, v190
	s_nop 0
	v_mul_f32_e32 v191, 0x45800000, v190
	v_cndmask_b32_e32 v160, v190, v191, vcc
	v_mul_f32_e32 v210, 0x4b800000, v207
	v_cmp_gt_f32_e64 s[8:9], s69, v207
	v_cmp_gt_f32_e32 vcc, s69, v206
	s_nop 0
	v_cndmask_b32_e64 v207, v207, v210, s[8:9]
	v_rsq_f32_e32 v207, v207
	s_nop 0
	v_mul_f32_e32 v210, 0x45800000, v207
	v_cndmask_b32_e64 v168, v207, v210, s[8:9]
	v_mul_f32_e32 v207, 0x4b800000, v206
	v_cndmask_b32_e32 v206, v206, v207, vcc
	v_rsq_f32_e32 v206, v206
	s_nop 0
	v_mul_f32_e32 v207, 0x45800000, v206
	v_cndmask_b32_e32 v164, v206, v207, vcc
	v_mul_f32_e32 v226, 0x4b800000, v223
	v_cmp_gt_f32_e64 s[8:9], s69, v223
	v_cmp_gt_f32_e32 vcc, s69, v222
	s_nop 0
	v_cndmask_b32_e64 v223, v223, v226, s[8:9]
	v_rsq_f32_e32 v223, v223
	s_nop 0
	v_mul_f32_e32 v226, 0x45800000, v223
	v_cndmask_b32_e64 v132, v223, v226, s[8:9]
	v_mul_f32_e32 v223, 0x4b800000, v222
	v_cndmask_b32_e32 v222, v222, v223, vcc
	v_rsq_f32_e32 v222, v222
	s_nop 0
	v_mul_f32_e32 v223, 0x45800000, v222
	v_cndmask_b32_e32 v130, v222, v223, vcc
	s_nop 0
	s_mov_b64 s[8:9], -1
	s_cmp_gt_i32 s70, 47
	s_cbranch_scc1 .LBB0_123
	s_andn2_b64 vcc, exec, s[8:9]
	s_cbranch_vccz .LBB0_126
